# diff-attention loop: block-A exps interleaved into the PV MFMA shadows and per-step K/V DMA staging moved from the loop head into block A
# speedup vs baseline: 1.0142x; 1.0123x over previous
.LBB0_502:
	s_add_i32 s37, s76, 1
	s_cmp_ge_u32 s37, s18
	s_cbranch_scc1 .Lhd_w0
	s_waitcnt vmcnt(4)
.Lhd_bar:
	s_barrier

.LBB0_508:
.LBB0_509:
	s_add_i32 s20, s2, 0xffffc000
	s_and_b32 s20, s20, 0xc000
	v_add_u32_e32 v238, s20, v234
	s_add_i32 s20, s65, s20
	v_mfma_f32_32x32x16_bf16 v[0:15], v[160:163], v[128:131], v[0:15]
	ds_read_b64_tr_b16 v[196:197], v238
	ds_read_b64_tr_b16 v[198:199], v238 offset:512
	v_add_u32_e32 v96, s20, v228
	v_add_u32_e32 v97, s20, v229
	v_add_u32_e32 v98, s20, v230
	v_add_u32_e32 v99, s20, v231
	v_exp_f32_e32 v241, v80
	v_exp_f32_e32 v242, v81
	v_mfma_f32_32x32x16_bf16 v[0:15], v[164:167], v[132:135], v[0:15]
	ds_read_b64_tr_b16 v[192:193], v238 offset:1024
	ds_read_b64_tr_b16 v[194:195], v238 offset:1536
	v_exp_f32_e32 v243, v82
	v_exp_f32_e32 v244, v83
	s_add_i32 s22, s76, 4
	s_cmp_ge_u32 s22, s19
	s_cbranch_scc1 .LstgK_skip
	s_and_b64 s[38:39], s[16:17], exec
	s_cselect_b32 s22, s22, s3
	s_ashr_i32 s23, s22, 31
	s_lshl_b64 s[22:23], s[22:23], 16
	s_add_u32 s22, s74, s22
	s_addc_u32 s23, s75, s23
	s_add_i32 s38, s2, 0x8000
	s_and_b32 s38, s38, 0xc000
	s_add_i32 s38, s54, s38
	s_mov_b32 s39, m0
	s_mov_b32 m0, s38
	s_nop 0
	global_load_lds_dwordx4 v204, s[22:23]
	s_mov_b32 m0, s39
	s_add_u32 s22, s22, 0x80
	s_addc_u32 s23, s23, 0
	s_addk_i32 s38, 0x2000
	s_mov_b32 s39, m0
	s_mov_b32 m0, s38
	s_nop 0
	global_load_lds_dwordx4 v204, s[22:23]
	s_mov_b32 m0, s39
.LstgK_skip:
	v_mfma_f32_32x32x16_bf16 v[32:47], v[160:163], v[136:139], v[32:47]
	ds_read_b64_tr_b16 v[188:189], v238 offset:4096
	ds_read_b64_tr_b16 v[190:191], v238 offset:4608
	v_exp_f32_e32 v245, v84
	v_exp_f32_e32 v246, v85
	v_add_f32_e32 v100, v243, v241
	v_add_f32_e32 v101, v244, v242
	v_mfma_f32_32x32x16_bf16 v[32:47], v[164:167], v[140:143], v[32:47]
	ds_read_b64_tr_b16 v[184:185], v238 offset:5120
	ds_read_b64_tr_b16 v[186:187], v238 offset:5632
	v_exp_f32_e32 v247, v86
	v_exp_f32_e32 v248, v87
	v_add_f32_e32 v100, v245, v100
	v_add_f32_e32 v101, v246, v101
	s_cmp_ge_u32 s37, s18
	s_cbranch_scc1 .LstgV_skip
	s_add_i32 s22, s76, 3
	s_add_i32 s23, s3, 1
	s_and_b64 s[20:21], s[16:17], exec
	s_cselect_b32 s20, s22, s23
	s_ashr_i32 s21, s20, 31
	s_lshl_b64 s[20:21], s[20:21], 16
	s_add_u32 s20, s80, s20
	s_addc_u32 s21, s81, s21
	s_add_i32 s22, s2, 0x4000
	s_and_b32 s22, s22, 0xc000
	s_add_i32 s22, s22, 0
	s_add_i32 s22, s22, 0x10000
	s_add_i32 s23, s22, s55
	s_mov_b32 s38, m0
	s_mov_b32 m0, s23
	s_nop 0
	global_load_lds_dwordx4 v226, s[20:21]
	s_mov_b32 m0, s38
	s_add_i32 s22, s22, s57
	s_mov_b32 s23, m0
	s_mov_b32 m0, s22
	s_nop 0
	global_load_lds_dwordx4 v227, s[20:21]
	s_mov_b32 m0, s23
.LstgV_skip:
	v_mfma_f32_32x32x16_bf16 v[48:63], v[160:163], v[144:147], v[48:63]
	ds_read_b64_tr_b16 v[180:181], v238 offset:8192
	ds_read_b64_tr_b16 v[182:183], v238 offset:8704
	v_exp_f32_e32 v249, v88
	v_exp_f32_e32 v250, v89
	v_add_f32_e32 v100, v247, v100
	v_add_f32_e32 v101, v248, v101
	v_mfma_f32_32x32x16_bf16 v[48:63], v[164:167], v[148:151], v[48:63]
	ds_read_b64_tr_b16 v[176:177], v238 offset:9216
	ds_read_b64_tr_b16 v[178:179], v238 offset:9728
	ds_read_b128 v[128:131], v96 offset:4096
	v_exp_f32_e32 v251, v90
	v_exp_f32_e32 v252, v91
	v_add_f32_e32 v100, v249, v100
	v_add_f32_e32 v101, v250, v101
	v_mfma_f32_32x32x16_bf16 v[16:31], v[160:163], v[152:155], v[16:31]
	ds_read_b64_tr_b16 v[172:173], v238 offset:12288
	ds_read_b64_tr_b16 v[174:175], v238 offset:12800
	v_exp_f32_e32 v253, v92
	v_exp_f32_e32 v239, v93
	v_add_f32_e32 v100, v251, v100
	v_add_f32_e32 v101, v252, v101
	v_mfma_f32_32x32x16_bf16 v[16:31], v[164:167], v[156:159], v[16:31]
	ds_read_b64_tr_b16 v[168:169], v238 offset:13312
	ds_read_b64_tr_b16 v[170:171], v238 offset:13824
	ds_read_b128 v[132:135], v97 offset:4096
	ds_read_b128 v[136:139], v98 offset:4096
	ds_read_b128 v[140:143], v99 offset:4096
	v_exp_f32_e32 v240, v94
	v_exp_f32_e32 v99, v95
	v_add_f32_e32 v100, v253, v100
	v_add_f32_e32 v101, v239, v101
	v_add_f32_e32 v100, v240, v100
	v_add_f32_e32 v101, v99, v101
	v_add_f32_e32 v100, v100, v101
	v_add_f32_e32 v235, v235, v100
	v_cvt_pk_bf16_f32 v156, v241, v242
	v_cvt_pk_bf16_f32 v157, v243, v244
	v_cvt_pk_bf16_f32 v158, v245, v246
	v_cvt_pk_bf16_f32 v159, v247, v248
	v_cvt_pk_bf16_f32 v162, v249, v250
	v_cvt_pk_bf16_f32 v163, v251, v252
	v_cvt_pk_bf16_f32 v164, v253, v239
	v_cvt_pk_bf16_f32 v165, v240, v99
	s_waitcnt lgkmcnt(7)
	v_mfma_f32_32x32x16_bf16 v[96:111], v[128:131], v[112:115], v[64:79]
	v_max3_f32 v144, v80, v81, v82
	v_max3_f32 v145, v83, v84, v85
	s_waitcnt lgkmcnt(2)
	v_mfma_f32_32x32x16_bf16 v[96:111], v[132:135], v[116:119], v[96:111]
	v_max3_f32 v128, v144, v86, v87
	v_max3_f32 v129, v145, v88, v89
	s_waitcnt lgkmcnt(1)
	v_mfma_f32_32x32x16_bf16 v[96:111], v[136:139], v[120:123], v[96:111]
	v_max3_f32 v128, v128, v90, v91
	v_max3_f32 v129, v129, v92, v93
	s_nop 0
	v_max3_f32 v128, v128, v94, v95
	s_waitcnt lgkmcnt(0)
	v_mfma_f32_32x32x16_bf16 v[96:111], v[140:143], v[124:127], v[96:111]
	v_max_f32_e32 v128, v128, v129
	ds_bpermute_b32 v129, v214, v128
	s_andn2_b64 vcc, exec, s[0:1]
	s_cbranch_vccz .LBB0_522
.LBB0_510:
	s_waitcnt lgkmcnt(0)
	v_max_f32_e32 v80, v128, v129
	v_cmp_lt_f32_e32 vcc, s67, v80
	s_cmp_lg_u64 vcc, 0
	s_cselect_b64 s[0:1], -1, 0
	s_cbranch_vccnz .LBB0_525
.LBB0_512:
	s_and_b32 s20, s2, 0xc000
	s_add_i32 s20, s65, s20
	v_mfma_f32_32x32x16_bf16 v[0:15], v[156:159], v[196:199], v[0:15]
	ds_read_b64_tr_b16 v[128:129], v238 offset:2048
	ds_read_b64_tr_b16 v[130:131], v238 offset:2560
	v_exp_f32_e32 v160, v96
	v_exp_f32_e32 v161, v97
	v_add_u32_e32 v152, s20, v228
	v_add_u32_e32 v239, s20, v229
	v_add_u32_e32 v240, s20, v230
	v_mfma_f32_32x32x16_bf16 v[0:15], v[162:165], v[192:195], v[0:15]
	ds_read_b64_tr_b16 v[132:133], v238 offset:3072
	ds_read_b64_tr_b16 v[134:135], v238 offset:3584
	v_exp_f32_e32 v166, v98
	v_exp_f32_e32 v167, v99
	v_mfma_f32_32x32x16_bf16 v[32:47], v[156:159], v[188:191], v[32:47]
	ds_read_b64_tr_b16 v[136:137], v238 offset:6144
	ds_read_b64_tr_b16 v[138:139], v238 offset:6656
	v_exp_f32_e32 v192, v100
	v_exp_f32_e32 v193, v101
	v_mfma_f32_32x32x16_bf16 v[32:47], v[162:165], v[184:187], v[32:47]
	ds_read_b64_tr_b16 v[140:141], v238 offset:7168
	ds_read_b64_tr_b16 v[142:143], v238 offset:7680
	v_exp_f32_e32 v188, v102
	v_exp_f32_e32 v189, v103
	v_mfma_f32_32x32x16_bf16 v[48:63], v[156:159], v[180:183], v[48:63]
	ds_read_b64_tr_b16 v[144:145], v238 offset:10240
	ds_read_b64_tr_b16 v[146:147], v238 offset:10752
	v_exp_f32_e32 v184, v104
	v_exp_f32_e32 v185, v105
	v_mfma_f32_32x32x16_bf16 v[48:63], v[162:165], v[176:179], v[48:63]
	ds_read_b64_tr_b16 v[148:149], v238 offset:11264
	ds_read_b64_tr_b16 v[150:151], v238 offset:11776
	ds_read_b128 v[180:183], v152
	v_exp_f32_e32 v186, v106
	v_exp_f32_e32 v187, v107
	v_mfma_f32_32x32x16_bf16 v[16:31], v[156:159], v[172:175], v[16:31]
	ds_read_b64_tr_b16 v[152:153], v238 offset:14336
	ds_read_b64_tr_b16 v[154:155], v238 offset:14848
	v_exp_f32_e32 v176, v108
	v_exp_f32_e32 v177, v109
	v_mfma_f32_32x32x16_bf16 v[16:31], v[162:165], v[168:171], v[16:31]
	ds_read_b64_tr_b16 v[156:157], v238 offset:15360
	ds_read_b64_tr_b16 v[158:159], v238 offset:15872
	v_add_f32_e32 v162, v166, v160
	v_add_f32_e32 v163, v167, v161
	v_exp_f32_e32 v178, v110
	v_exp_f32_e32 v179, v111
	v_pk_add_f32 v[164:165], v[192:193], v[162:163]
	ds_read_b128 v[168:171], v239
	ds_read_b128 v[172:175], v240
	v_pk_add_f32 v[164:165], v[188:189], v[164:165]
	v_cvt_pk_bf16_f32 v160, v160, v161
	v_cvt_pk_bf16_f32 v161, v166, v167
	v_pk_add_f32 v[166:167], v[184:185], v[164:165]
	v_cvt_pk_bf16_f32 v162, v192, v193
	v_pk_add_f32 v[166:167], v[186:187], v[166:167]
	v_cvt_pk_bf16_f32 v163, v188, v189
	v_cvt_pk_bf16_f32 v164, v184, v185
	v_cvt_pk_bf16_f32 v165, v186, v187
	v_pk_add_f32 v[184:185], v[176:177], v[166:167]
	v_cvt_pk_bf16_f32 v166, v176, v177
	v_cvt_pk_bf16_f32 v167, v178, v179
	v_pk_add_f32 v[176:177], v[178:179], v[184:185]
	s_waitcnt lgkmcnt(6)
	v_mfma_f32_32x32x16_bf16 v[80:95], v[180:183], v[112:115], v[64:79]
	v_max3_f32 v178, v96, v97, v98
	v_add_f32_e32 v96, v176, v177
	v_add_f32_e32 v235, v235, v96
	v_add_u32_e32 v96, s20, v231
	v_max3_f32 v100, v99, v100, v101
	ds_read_b128 v[96:99], v96
	s_waitcnt lgkmcnt(2)
	v_mfma_f32_32x32x16_bf16 v[80:95], v[168:171], v[116:119], v[80:95]
	v_max3_f32 v101, v178, v102, v103
	v_max3_f32 v100, v100, v104, v105
	s_waitcnt lgkmcnt(1)
	v_mfma_f32_32x32x16_bf16 v[80:95], v[172:175], v[120:123], v[80:95]
	v_max3_f32 v101, v101, v106, v107
	v_max3_f32 v100, v100, v108, v109
	s_nop 0
	v_max3_f32 v101, v101, v110, v111
	v_max_f32_e32 v100, v101, v100
	s_waitcnt lgkmcnt(0)
	v_mfma_f32_32x32x16_bf16 v[80:95], v[96:99], v[124:127], v[80:95]
	ds_bpermute_b32 v101, v214, v100
	s_waitcnt lgkmcnt(0)
	v_max_f32_e32 v96, v100, v101
	s_addk_i32 s2, 0x4000
	s_add_i32 s3, s3, -1
	s_cmp_ge_u32 s37, s84
	s_cbranch_scc1 .LBB0_527
	s_mov_b32 s76, s37
	s_branch .LBB0_502
.Lhd_w0:
	s_waitcnt vmcnt(0)
	s_branch .Lhd_bar
